# code placement: attention, mix and norm loop heads also aligned to 64 bytes
# baseline (speedup 1.0000x reference)
.LBB0_164:
	s_mul_i32 s2, s36, 0x8800
	v_add_u32_e32 v0, s2, v92
	v_add_u32_e32 v38, v0, v101
	ds_read_b128 v[62:65], v38 offset:34816
	ds_read_b128 v[66:69], v38 offset:35904
	v_add_u32_e32 v38, v0, v102
	ds_read_b128 v[46:49], v38 offset:34816
	ds_read_b128 v[50:53], v38 offset:35904
	v_add_u32_e32 v38, v0, v103
	v_add_u32_e32 v0, v0, v104
	ds_read_b128 v[54:57], v38 offset:34816
	ds_read_b128 v[58:61], v38 offset:35904
	ds_read_b128 v[42:45], v0 offset:34816
	ds_read_b128 v[38:41], v0 offset:35904
	ds_read_b128 v[122:125], v114
	s_waitcnt lgkmcnt(0)
	v_mfma_f32_16x16x32_bf16 v[126:129], v[62:65], v[122:125], 0
	s_waitcnt vmcnt(0)
	v_lshlrev_b32_e32 v132, 16, v34
	v_and_b32_e32 v34, 0xffff0000, v34
	v_or_b32_e32 v0, s37, v5
	s_nop 3
	v_add_f32_e32 v126, v121, v126
	v_add_f32_e32 v127, v121, v127
	v_mfma_f32_16x16x32_bf16 v[122:125], v[66:69], v[122:125], 0
	v_mul_f32_e32 v126, v126, v132
	v_mul_f32_e32 v34, v127, v34
	v_cvt_pk_bf16_f32 v34, v126, v34
	v_lshlrev_b32_e32 v126, 16, v35
	v_add_f32_e32 v127, v121, v128
	v_mul_f32_e32 v126, v127, v126
	v_and_b32_e32 v35, 0xffff0000, v35
	v_add_f32_e32 v127, v121, v129
	v_mul_f32_e32 v35, v127, v35
	v_cvt_pk_bf16_f32 v35, v126, v35
	v_lshlrev_b32_e32 v126, 16, v36
	v_add_f32_e32 v122, v121, v122
	v_and_b32_e32 v36, 0xffff0000, v36
	v_add_f32_e32 v123, v121, v123
	v_or_b32_e32 v130, s25, v0
	v_mul_f32_e32 v122, v122, v126
	v_mul_f32_e32 v36, v123, v36
	v_ashrrev_i32_e32 v131, 31, v130
	v_cvt_pk_bf16_f32 v36, v122, v36
	v_lshlrev_b32_e32 v122, 16, v37
	v_add_f32_e32 v123, v121, v124
	v_and_b32_e32 v37, 0xffff0000, v37
	v_add_f32_e32 v121, v121, v125
	v_lshlrev_b64 v[130:131], 12, v[130:131]
	v_mul_f32_e32 v37, v121, v37
	v_lshl_add_u64 v[130:131], v[88:89], 0, v[130:131]
	v_mul_f32_e32 v122, v123, v122
	v_cvt_pk_bf16_f32 v37, v122, v37
	global_store_dwordx4 v[130:131], v[34:37], off
	ds_read_b128 v[34:37], v115
	ds_read_b128 v[126:129], v115 offset:64
	s_waitcnt lgkmcnt(1)
	v_mfma_f32_16x16x32_bf16 v[122:125], v[62:65], v[34:37], 0
	v_lshlrev_b32_e32 v121, 16, v30
	v_and_b32_e32 v30, 0xffff0000, v30
	s_add_i32 s31, s31, s70
	s_waitcnt lgkmcnt(0)
	v_mfma_f32_16x16x32_bf16 v[122:125], v[46:49], v[126:129], v[122:125]
	s_and_b64 vcc, exec, s[22:23]
	s_mov_b32 s38, s35
	s_mov_b32 s41, s34
	v_mfma_f32_16x16x32_bf16 v[34:37], v[66:69], v[34:37], 0
	s_mov_b32 s36, s39
	s_nop 2
	v_add_f32_e32 v122, v120, v122
	v_mul_f32_e32 v121, v122, v121
	v_add_f32_e32 v122, v120, v123
	v_mfma_f32_16x16x32_bf16 v[34:37], v[50:53], v[126:129], v[34:37]
	v_mul_f32_e32 v30, v122, v30
	v_cvt_pk_bf16_f32 v30, v121, v30
	v_lshlrev_b32_e32 v121, 16, v31
	v_add_f32_e32 v122, v120, v124
	v_mul_f32_e32 v121, v122, v121
	v_and_b32_e32 v31, 0xffff0000, v31
	v_add_f32_e32 v122, v120, v125
	v_mul_f32_e32 v31, v122, v31
	v_cvt_pk_bf16_f32 v31, v121, v31
	v_lshlrev_b32_e32 v121, 16, v32
	v_add_f32_e32 v34, v120, v34
	v_and_b32_e32 v32, 0xffff0000, v32
	v_add_f32_e32 v35, v120, v35
	v_mul_f32_e32 v34, v34, v121
	v_mul_f32_e32 v32, v35, v32
	v_or_b32_e32 v126, s26, v0
	v_cvt_pk_bf16_f32 v32, v34, v32
	v_lshlrev_b32_e32 v34, 16, v33
	v_add_f32_e32 v35, v120, v36
	v_ashrrev_i32_e32 v127, 31, v126
	v_mul_f32_e32 v34, v35, v34
	v_and_b32_e32 v33, 0xffff0000, v33
	v_add_f32_e32 v35, v120, v37
	v_lshlrev_b64 v[126:127], 12, v[126:127]
	v_mul_f32_e32 v33, v35, v33
	v_lshl_add_u64 v[126:127], v[88:89], 0, v[126:127]
	v_cvt_pk_bf16_f32 v33, v34, v33
	global_store_dwordx4 v[126:127], v[30:33], off
	ds_read_b128 v[30:33], v116
	ds_read_b128 v[120:123], v116 offset:64
	s_waitcnt lgkmcnt(1)
	v_mfma_f32_16x16x32_bf16 v[34:37], v[62:65], v[30:33], 0
	v_mfma_f32_16x16x32_bf16 v[30:33], v[66:69], v[30:33], 0
	s_waitcnt lgkmcnt(0)
	v_mfma_f32_16x16x32_bf16 v[34:37], v[46:49], v[120:123], v[34:37]
	v_mfma_f32_16x16x32_bf16 v[30:33], v[50:53], v[120:123], v[30:33]
	ds_read_b128 v[120:123], v116 offset:128
	s_waitcnt lgkmcnt(0)
	v_mfma_f32_16x16x32_bf16 v[34:37], v[54:57], v[120:123], v[34:37]
	v_mfma_f32_16x16x32_bf16 v[30:33], v[58:61], v[120:123], v[30:33]
	v_lshlrev_b32_e32 v122, 16, v26
	s_nop 5
	v_add_f32_e32 v34, v119, v34
	v_and_b32_e32 v26, 0xffff0000, v26
	v_add_f32_e32 v35, v119, v35
	v_mul_f32_e32 v34, v34, v122
	v_mul_f32_e32 v26, v35, v26
	v_cvt_pk_bf16_f32 v26, v34, v26
	v_lshlrev_b32_e32 v34, 16, v27
	v_add_f32_e32 v35, v119, v36
	v_mul_f32_e32 v34, v35, v34
	v_and_b32_e32 v27, 0xffff0000, v27
	v_add_f32_e32 v35, v119, v37
	v_mul_f32_e32 v27, v35, v27
	v_cvt_pk_bf16_f32 v27, v34, v27
	v_lshlrev_b32_e32 v34, 16, v28
	v_add_f32_e32 v30, v119, v30
	v_and_b32_e32 v28, 0xffff0000, v28
	v_add_f32_e32 v31, v119, v31
	v_mul_f32_e32 v30, v30, v34
	v_mul_f32_e32 v28, v31, v28
	v_or_b32_e32 v120, s27, v0
	v_cvt_pk_bf16_f32 v28, v30, v28
	v_lshlrev_b32_e32 v30, 16, v29
	v_add_f32_e32 v31, v119, v32
	v_ashrrev_i32_e32 v121, 31, v120
	v_mul_f32_e32 v30, v31, v30
	v_and_b32_e32 v29, 0xffff0000, v29
	v_add_f32_e32 v31, v119, v33
	v_lshlrev_b64 v[120:121], 12, v[120:121]
	v_mul_f32_e32 v29, v31, v29
	v_lshl_add_u64 v[120:121], v[88:89], 0, v[120:121]
	v_cvt_pk_bf16_f32 v29, v30, v29
	global_store_dwordx4 v[120:121], v[26:29], off
	ds_read_b128 v[26:29], v117
	ds_read_b128 v[34:37], v117 offset:64
	s_waitcnt lgkmcnt(1)
	v_mfma_f32_16x16x32_bf16 v[30:33], v[62:65], v[26:29], 0
	v_mfma_f32_16x16x32_bf16 v[26:29], v[66:69], v[26:29], 0
	s_waitcnt lgkmcnt(0)
	v_mfma_f32_16x16x32_bf16 v[30:33], v[46:49], v[34:37], v[30:33]
	v_mfma_f32_16x16x32_bf16 v[26:29], v[50:53], v[34:37], v[26:29]
	ds_read_b128 v[34:37], v117 offset:128
	s_waitcnt lgkmcnt(0)
	v_mfma_f32_16x16x32_bf16 v[30:33], v[54:57], v[34:37], v[30:33]
	v_mfma_f32_16x16x32_bf16 v[26:29], v[58:61], v[34:37], v[26:29]
	ds_read_b128 v[34:37], v117 offset:192
	s_waitcnt lgkmcnt(0)
	v_mfma_f32_16x16x32_bf16 v[30:33], v[42:45], v[34:37], v[30:33]
	v_mfma_f32_16x16x32_bf16 v[26:29], v[38:41], v[34:37], v[26:29]
	v_or_b32_e32 v34, s28, v0
	v_lshlrev_b32_e32 v0, 16, v22
	s_nop 4
	v_add_f32_e32 v30, v118, v30
	v_mul_f32_e32 v0, v30, v0
	v_and_b32_e32 v22, 0xffff0000, v22
	v_add_f32_e32 v30, v118, v31
	v_mul_f32_e32 v22, v30, v22
	v_cvt_pk_bf16_f32 v22, v0, v22
	v_lshlrev_b32_e32 v0, 16, v23
	v_add_f32_e32 v30, v118, v32
	v_mul_f32_e32 v0, v30, v0
	v_and_b32_e32 v23, 0xffff0000, v23
	v_add_f32_e32 v30, v118, v33
	v_mul_f32_e32 v23, v30, v23
	v_cvt_pk_bf16_f32 v23, v0, v23
	v_lshlrev_b32_e32 v0, 16, v24
	v_add_f32_e32 v26, v118, v26
	v_mul_f32_e32 v0, v26, v0
	v_and_b32_e32 v24, 0xffff0000, v24
	v_add_f32_e32 v26, v118, v27
	v_mul_f32_e32 v24, v26, v24
	v_ashrrev_i32_e32 v35, 31, v34
	v_cvt_pk_bf16_f32 v24, v0, v24
	v_lshlrev_b32_e32 v0, 16, v25
	v_add_f32_e32 v26, v118, v28
	v_lshlrev_b64 v[34:35], 12, v[34:35]
	v_mul_f32_e32 v0, v26, v0
	v_and_b32_e32 v25, 0xffff0000, v25
	v_add_f32_e32 v26, v118, v29
	v_lshl_add_u64 v[34:35], v[88:89], 0, v[34:35]
	v_mul_f32_e32 v25, v26, v25
	v_cvt_pk_bf16_f32 v25, v0, v25
	global_store_dwordx4 v[34:35], v[22:25], off
	s_waitcnt lgkmcnt(0)
	s_barrier
	s_cbranch_vccnz .LBB0_180
	.p2align	6

.LBB0_317:
	s_waitcnt lgkmcnt(0)
	s_barrier
	s_add_i32 s33, s33, s40
	s_add_i32 s41, s41, s10
	s_cmpk_gt_i32 s33, 0x3ff
	s_cbranch_scc1 .LBB0_332
	.p2align	6

.LBB0_606:
	s_add_i32 s20, s20, 2
	s_add_i32 s12, s12, s23
	s_cmp_ge_i32 s20, s18
	s_cbranch_scc1 .LBB0_630
	.p2align	6
